# FF1 epilogue stores of H marked nt (streaming) to keep weights and A tiles in L2
# speedup vs baseline: 1.0045x; 1.0045x over previous
; #define PG8_STAGE(bufoff, gbase, voff) do { _Pragma("unroll") for (int _i = 0; _i < 2; ++_i) \
;     __builtin_amdgcn_global_load_lds((const unsigned*)((const char*)(gbase) + (voff)[_i]), (LAS unsigned*)(lds + (bufoff) + ldsw + _i * 8192), 16, 0, 0); } while (0)
; #define PG8_LDA(dst, b, h) do { _Pragma("unroll") for (int m = 0; m < 4; ++m) _Pragma("unroll") for (int k = 0; k < 2; ++k) dst[m][k] = *(const LAS bf16x8*)(lds + PG8_SA(b, h) + aoff + m * 2048 + k * 1024); } while (0)
; #define PG8_LDB(dst, b, h) do { _Pragma("unroll") for (int n = 0; n < 2; ++n) _Pragma("unroll") for (int k = 0; k < 2; ++k) dst[n][k] = *(const LAS bf16x8*)(lds + PG8_SB(b, h) + boff + n * 2048 + k * 1024); } while (0)
; #define PG8_MMA(ai, bj, At, Bt) do { __builtin_amdgcn_s_setprio(1); _Pragma("unroll") for (int m = 0; m < 4; ++m) _Pragma("unroll") for (int n = 0; n < 2; ++n) _Pragma("unroll") for (int k = 0; k < 2; ++k) \
;     acc[ai][bj][m][n] = __builtin_amdgcn_mfma_f32_16x16x32_bf16(Bt[n][k], At[m][k], acc[ai][bj][m][n], 0, 0, 0); __builtin_amdgcn_s_setprio(0); } while (0)
; #define PG8_WAIT_V(n) asm volatile("s_waitcnt vmcnt(" #n ")" ::: "memory")
; #define PG8_WAIT_L(n) asm volatile("s_waitcnt lgkmcnt(" #n ")" ::: "memory")
; #define PG8_BAR __builtin_amdgcn_s_barrier()
; #define PG8_SCHED __builtin_amdgcn_sched_barrier(0)
; template <class Epi>
; __device__ __forceinline__ void gemm_phase(LAS unsigned char* lds, const Gemm g, const StaticOrder& S, const Epi& E) {
;     ...
;       PG8_LDB(B0, 0, 0); PG8_SCHED; PG8_LDA(At, 0, 0); PG8_STAGE(PG8_SA(1, 1), a1 + hstepA, voffA);
;       PG8_WAIT_L(8); PG8_BAR; PG8_WAIT_L(0); PG8_MMA(0, 0, At, B0); PG8_BAR; PG8_SCHED;
;       PG8_LDB(B1, 0, 1); PG8_STAGE(PG8_SB(0, 0), b2, voffB);
;       PG8_BAR; PG8_WAIT_L(0); PG8_MMA(0, 1, At, B1); PG8_BAR;
;       PG8_LDA(At, 0, 1); PG8_STAGE(PG8_SA(0, 0), a2, voffA);
;       PG8_BAR; PG8_WAIT_L(0); PG8_MMA(1, 0, At, B0); PG8_BAR; PG8_SCHED;
;       PG8_STAGE(PG8_SB(0, 1), b2 + hstepB, voffB);
;       PG8_WAIT_V(6); PG8_BAR; PG8_MMA(1, 1, At, B1); PG8_BAR;
.LBB0_3803:
	s_add_u32 s20, s14, 0xfffc0080
	s_addc_u32 s21, s15, -1
	s_add_i32 s46, 0, 0x10000
	v_add_u32_e32 v145, s46, v143
	ds_read_b128 v[146:149], v145
	ds_read_b128 v[150:153], v145 offset:1024
	ds_read_b128 v[154:157], v145 offset:2048
	ds_read_b128 v[158:161], v145 offset:3072
	s_cmp_eq_u32 s45, 12
	s_cselect_b32 s23, s5, s21
	s_cselect_b32 s22, s41, s20
	s_cselect_b32 s21, s3, s44
	s_cselect_b32 s20, s42, s43
	v_lshl_add_u64 v[194:195], s[14:15], 0, v[138:139]
	s_add_i32 m0, s30, 0xc000
	ds_read_b128 v[162:165], v144
	ds_read_b128 v[166:169], v144 offset:1024
	ds_read_b128 v[170:173], v144 offset:2048
	ds_read_b128 v[174:177], v144 offset:3072
	ds_read_b128 v[178:181], v144 offset:4096
	ds_read_b128 v[182:185], v144 offset:5120
	ds_read_b128 v[186:189], v144 offset:6144
	ds_read_b128 v[190:193], v144 offset:7168
	global_load_lds_dwordx4 v[194:195], off
	v_lshl_add_u64 v[194:195], s[14:15], 0, v[140:141]
	s_add_i32 m0, s30, 0xe000
	s_nop 0
	global_load_lds_dwordx4 v[194:195], off
	s_waitcnt lgkmcnt(8)
	s_barrier
	s_waitcnt lgkmcnt(0)
	s_setprio 1
	s_waitcnt lgkmcnt(0)
	v_mfma_f32_16x16x32_bf16 v[126:129], v[146:149], v[162:165], v[126:129]
	v_mfma_f32_16x16x32_bf16 v[122:125], v[154:157], v[162:165], v[122:125]
	v_mfma_f32_16x16x32_bf16 v[110:113], v[146:149], v[170:173], v[110:113]
	v_mfma_f32_16x16x32_bf16 v[106:109], v[154:157], v[170:173], v[106:109]
	v_mfma_f32_16x16x32_bf16 v[94:97], v[146:149], v[178:181], v[94:97]
	v_mfma_f32_16x16x32_bf16 v[90:93], v[154:157], v[178:181], v[90:93]
	v_mfma_f32_16x16x32_bf16 v[78:81], v[146:149], v[186:189], v[78:81]
	v_mfma_f32_16x16x32_bf16 v[74:77], v[154:157], v[186:189], v[74:77]
	v_mfma_f32_16x16x32_bf16 v[126:129], v[150:153], v[166:169], v[126:129]
	v_mfma_f32_16x16x32_bf16 v[122:125], v[158:161], v[166:169], v[122:125]
	v_mfma_f32_16x16x32_bf16 v[110:113], v[150:153], v[174:177], v[110:113]
	v_mfma_f32_16x16x32_bf16 v[106:109], v[158:161], v[174:177], v[106:109]
	v_mfma_f32_16x16x32_bf16 v[94:97], v[150:153], v[182:185], v[94:97]
	v_mfma_f32_16x16x32_bf16 v[90:93], v[158:161], v[182:185], v[90:93]
	v_mfma_f32_16x16x32_bf16 v[78:81], v[150:153], v[190:193], v[78:81]
	v_mfma_f32_16x16x32_bf16 v[74:77], v[158:161], v[190:193], v[74:77]
	s_setprio 0
	s_barrier
	s_add_i32 s48, 0, 0x14000
	s_add_i32 s46, s46, s29
	v_add_u32_e32 v145, s48, v143
	v_lshl_add_u64 v[210:211], s[20:21], 0, v[134:135]
	s_mov_b32 m0, s46
	ds_read_b128 v[194:197], v145
	ds_read_b128 v[198:201], v145 offset:1024
	ds_read_b128 v[202:205], v145 offset:2048
	ds_read_b128 v[206:209], v145 offset:3072
	global_load_lds_dwordx4 v[210:211], off
	v_lshl_add_u64 v[212:213], s[20:21], 0, v[130:131]
	s_add_i32 m0, s46, 0x2000
	s_nop 0
	global_load_lds_dwordx4 v[212:213], off
	s_barrier
	s_waitcnt lgkmcnt(0)
	s_setprio 1
	s_waitcnt lgkmcnt(0)
	v_mfma_f32_16x16x32_bf16 v[118:121], v[194:197], v[162:165], v[118:121]
	v_mfma_f32_16x16x32_bf16 v[114:117], v[202:205], v[162:165], v[114:117]
	v_mfma_f32_16x16x32_bf16 v[102:105], v[194:197], v[170:173], v[102:105]
	v_mfma_f32_16x16x32_bf16 v[98:101], v[202:205], v[170:173], v[98:101]
	v_mfma_f32_16x16x32_bf16 v[86:89], v[194:197], v[178:181], v[86:89]
	v_mfma_f32_16x16x32_bf16 v[82:85], v[202:205], v[178:181], v[82:85]
	v_mfma_f32_16x16x32_bf16 v[70:73], v[194:197], v[186:189], v[70:73]
	v_mfma_f32_16x16x32_bf16 v[66:69], v[202:205], v[186:189], v[66:69]
	v_mfma_f32_16x16x32_bf16 v[118:121], v[198:201], v[166:169], v[118:121]
	v_mfma_f32_16x16x32_bf16 v[114:117], v[206:209], v[166:169], v[114:117]
	v_mfma_f32_16x16x32_bf16 v[102:105], v[198:201], v[174:177], v[102:105]
	v_mfma_f32_16x16x32_bf16 v[98:101], v[206:209], v[174:177], v[98:101]
	v_mfma_f32_16x16x32_bf16 v[86:89], v[198:201], v[182:185], v[86:89]
	v_mfma_f32_16x16x32_bf16 v[82:85], v[206:209], v[182:185], v[82:85]
	v_mfma_f32_16x16x32_bf16 v[70:73], v[198:201], v[190:193], v[70:73]
	v_mfma_f32_16x16x32_bf16 v[66:69], v[206:209], v[190:193], v[66:69]
	s_setprio 0
	s_mov_b32 m0, s30
	v_lshl_add_u64 v[214:215], s[22:23], 0, v[136:137]
	s_barrier
	ds_read_b128 v[162:165], v144 offset:16384
	ds_read_b128 v[166:169], v144 offset:17408
	ds_read_b128 v[170:173], v144 offset:18432
	ds_read_b128 v[174:177], v144 offset:19456
	ds_read_b128 v[178:181], v144 offset:20480
	ds_read_b128 v[182:185], v144 offset:21504
	ds_read_b128 v[186:189], v144 offset:22528
	ds_read_b128 v[190:193], v144 offset:23552
	global_load_lds_dwordx4 v[214:215], off
	v_lshl_add_u64 v[216:217], s[22:23], 0, v[132:133]
	s_mov_b32 m0, s31
	s_nop 0
	global_load_lds_dwordx4 v[216:217], off
	s_barrier
	s_waitcnt lgkmcnt(0)
	s_setprio 1
	s_waitcnt lgkmcnt(0)
	v_mfma_f32_16x16x32_bf16 v[62:65], v[146:149], v[162:165], v[62:65]
	v_mfma_f32_16x16x32_bf16 v[58:61], v[154:157], v[162:165], v[58:61]
	v_mfma_f32_16x16x32_bf16 v[46:49], v[146:149], v[170:173], v[46:49]
	v_mfma_f32_16x16x32_bf16 v[42:45], v[154:157], v[170:173], v[42:45]
	v_mfma_f32_16x16x32_bf16 v[30:33], v[146:149], v[178:181], v[30:33]
	v_mfma_f32_16x16x32_bf16 v[26:29], v[154:157], v[178:181], v[26:29]
	v_mfma_f32_16x16x32_bf16 v[12:15], v[146:149], v[186:189], v[12:15]
	v_mfma_f32_16x16x32_bf16 v[8:11], v[154:157], v[186:189], v[8:11]
	v_mfma_f32_16x16x32_bf16 v[62:65], v[150:153], v[166:169], v[62:65]
	v_mfma_f32_16x16x32_bf16 v[58:61], v[158:161], v[166:169], v[58:61]
	v_mfma_f32_16x16x32_bf16 v[46:49], v[150:153], v[174:177], v[46:49]
	v_mfma_f32_16x16x32_bf16 v[42:45], v[158:161], v[174:177], v[42:45]
	v_mfma_f32_16x16x32_bf16 v[30:33], v[150:153], v[182:185], v[30:33]
	v_mfma_f32_16x16x32_bf16 v[26:29], v[158:161], v[182:185], v[26:29]
	v_mfma_f32_16x16x32_bf16 v[12:15], v[150:153], v[190:193], v[12:15]
	v_mfma_f32_16x16x32_bf16 v[8:11], v[158:161], v[190:193], v[8:11]
	s_setprio 0
	s_barrier
; #define PG8_STAGE(bufoff, gbase, voff) do { _Pragma("unroll") for (int _i = 0; _i < 2; ++_i) \
;     __builtin_amdgcn_global_load_lds((const unsigned*)((const char*)(gbase) + (voff)[_i]), (LAS unsigned*)(lds + (bufoff) + ldsw + _i * 8192), 16, 0, 0); } while (0)
; #define PG8_LDA(dst, b, h) do { _Pragma("unroll") for (int m = 0; m < 4; ++m) _Pragma("unroll") for (int k = 0; k < 2; ++k) dst[m][k] = *(const LAS bf16x8*)(lds + PG8_SA(b, h) + aoff + m * 2048 + k * 1024); } while (0)
; #define PG8_LDB(dst, b, h) do { _Pragma("unroll") for (int n = 0; n < 2; ++n) _Pragma("unroll") for (int k = 0; k < 2; ++k) dst[n][k] = *(const LAS bf16x8*)(lds + PG8_SB(b, h) + boff + n * 2048 + k * 1024); } while (0)
; #define PG8_MMA(ai, bj, At, Bt) do { __builtin_amdgcn_s_setprio(1); _Pragma("unroll") for (int m = 0; m < 4; ++m) _Pragma("unroll") for (int n = 0; n < 2; ++n) _Pragma("unroll") for (int k = 0; k < 2; ++k) \
;     acc[ai][bj][m][n] = __builtin_amdgcn_mfma_f32_16x16x32_bf16(Bt[n][k], At[m][k], acc[ai][bj][m][n], 0, 0, 0); __builtin_amdgcn_s_setprio(0); } while (0)
; #define PG8_WAIT_V(n) asm volatile("s_waitcnt vmcnt(" #n ")" ::: "memory")
; #define PG8_WAIT_L(n) asm volatile("s_waitcnt lgkmcnt(" #n ")" ::: "memory")
; #define PG8_BAR __builtin_amdgcn_s_barrier()
; #define PG8_SCHED __builtin_amdgcn_sched_barrier(0)
; template <class Epi>
; __device__ __forceinline__ void gemm_phase(LAS unsigned char* lds, const Gemm g, const StaticOrder& S, const Epi& E) {
;     ...
;       PG8_STAGE(PG8_SB(0, 1), b2 + hstepB, voffB);
;       PG8_WAIT_V(6); PG8_BAR; PG8_MMA(1, 1, At, B1); PG8_BAR;
;       PG8_LDB(B0, 1, 0); PG8_SCHED; PG8_LDA(At, 1, 0); PG8_STAGE(PG8_SA(0, 1), a2 + hstepA, voffA);
;       PG8_WAIT_L(8); PG8_BAR; PG8_WAIT_L(0); PG8_MMA(0, 0, At, B0); PG8_BAR; PG8_SCHED;
;       PG8_LDB(B1, 1, 1); PG8_STAGE(PG8_SB(1, 0), b3, voffB);
;       PG8_BAR; PG8_WAIT_L(0); PG8_MMA(0, 1, At, B1); PG8_BAR;
;       PG8_LDA(At, 1, 1); PG8_STAGE(PG8_SA(1, 0), a3, voffA);
	s_add_u32 s46, s20, 0x40000
	s_addc_u32 s47, s21, 0
	s_add_i32 s48, s48, s29
	v_lshl_add_u64 v[146:147], s[46:47], 0, v[134:135]
	s_mov_b32 m0, s48
	s_nop 0
	global_load_lds_dwordx4 v[146:147], off
	v_lshl_add_u64 v[146:147], s[46:47], 0, v[130:131]
	s_add_i32 m0, s48, 0x2000
	s_nop 0
	global_load_lds_dwordx4 v[146:147], off
	s_waitcnt vmcnt(6)
	s_barrier
	s_setprio 1
	v_mfma_f32_16x16x32_bf16 v[54:57], v[194:197], v[162:165], v[54:57]
	v_mfma_f32_16x16x32_bf16 v[50:53], v[202:205], v[162:165], v[50:53]
	v_mfma_f32_16x16x32_bf16 v[38:41], v[194:197], v[170:173], v[38:41]
	v_mfma_f32_16x16x32_bf16 v[34:37], v[202:205], v[170:173], v[34:37]
	v_mfma_f32_16x16x32_bf16 v[22:25], v[194:197], v[178:181], v[22:25]
	v_mfma_f32_16x16x32_bf16 v[18:21], v[202:205], v[178:181], v[18:21]
	v_mfma_f32_16x16x32_bf16 v[4:7], v[194:197], v[186:189], v[4:7]
	v_mfma_f32_16x16x32_bf16 v[0:3], v[202:205], v[186:189], v[0:3]
	v_mfma_f32_16x16x32_bf16 v[54:57], v[198:201], v[166:169], v[54:57]
	v_mfma_f32_16x16x32_bf16 v[50:53], v[206:209], v[166:169], v[50:53]
	v_mfma_f32_16x16x32_bf16 v[38:41], v[198:201], v[174:177], v[38:41]
	v_mfma_f32_16x16x32_bf16 v[34:37], v[206:209], v[174:177], v[34:37]
	v_mfma_f32_16x16x32_bf16 v[22:25], v[198:201], v[182:185], v[22:25]
	v_mfma_f32_16x16x32_bf16 v[18:21], v[206:209], v[182:185], v[18:21]
	v_mfma_f32_16x16x32_bf16 v[4:7], v[198:201], v[190:193], v[4:7]
	v_mfma_f32_16x16x32_bf16 v[0:3], v[206:209], v[190:193], v[0:3]
	s_setprio 0
	s_add_i32 s46, 0, 0x18000
	v_add_u32_e32 v145, s46, v143
	s_barrier
	ds_read_b128 v[146:149], v145
	ds_read_b128 v[150:153], v145 offset:1024
	ds_read_b128 v[154:157], v145 offset:2048
	ds_read_b128 v[158:161], v145 offset:3072
	s_add_u32 s22, s22, 0x40000
	s_addc_u32 s23, s23, 0
	s_mov_b32 m0, s34
	v_lshl_add_u64 v[194:195], s[22:23], 0, v[136:137]
	ds_read_b128 v[162:165], v144 offset:32768
	ds_read_b128 v[166:169], v144 offset:33792
	ds_read_b128 v[170:173], v144 offset:34816
	ds_read_b128 v[174:177], v144 offset:35840
	ds_read_b128 v[178:181], v144 offset:36864
	ds_read_b128 v[182:185], v144 offset:37888
	ds_read_b128 v[186:189], v144 offset:38912
	ds_read_b128 v[190:193], v144 offset:39936
	global_load_lds_dwordx4 v[194:195], off
	v_lshl_add_u64 v[194:195], s[22:23], 0, v[132:133]
	s_mov_b32 m0, s35
	s_nop 0
	global_load_lds_dwordx4 v[194:195], off
	s_waitcnt lgkmcnt(8)
	s_barrier
	s_waitcnt lgkmcnt(0)
	s_setprio 1
	s_waitcnt lgkmcnt(0)
	v_mfma_f32_16x16x32_bf16 v[126:129], v[146:149], v[162:165], v[126:129]
	v_mfma_f32_16x16x32_bf16 v[122:125], v[154:157], v[162:165], v[122:125]
	v_mfma_f32_16x16x32_bf16 v[110:113], v[146:149], v[170:173], v[110:113]
	v_mfma_f32_16x16x32_bf16 v[106:109], v[154:157], v[170:173], v[106:109]
	v_mfma_f32_16x16x32_bf16 v[94:97], v[146:149], v[178:181], v[94:97]
	v_mfma_f32_16x16x32_bf16 v[90:93], v[154:157], v[178:181], v[90:93]
	v_mfma_f32_16x16x32_bf16 v[78:81], v[146:149], v[186:189], v[78:81]
	v_mfma_f32_16x16x32_bf16 v[74:77], v[154:157], v[186:189], v[74:77]
	v_mfma_f32_16x16x32_bf16 v[126:129], v[150:153], v[166:169], v[126:129]
	v_mfma_f32_16x16x32_bf16 v[122:125], v[158:161], v[166:169], v[122:125]
	v_mfma_f32_16x16x32_bf16 v[110:113], v[150:153], v[174:177], v[110:113]
	v_mfma_f32_16x16x32_bf16 v[106:109], v[158:161], v[174:177], v[106:109]
	v_mfma_f32_16x16x32_bf16 v[94:97], v[150:153], v[182:185], v[94:97]
	v_mfma_f32_16x16x32_bf16 v[90:93], v[158:161], v[182:185], v[90:93]
	v_mfma_f32_16x16x32_bf16 v[78:81], v[150:153], v[190:193], v[78:81]
	v_mfma_f32_16x16x32_bf16 v[74:77], v[158:161], v[190:193], v[74:77]
	s_setprio 0
	s_barrier
	s_add_i32 s22, 0, 0x1c000
	s_add_i32 s23, s46, s29
	v_add_u32_e32 v145, s22, v143
	v_lshl_add_u64 v[210:211], v[210:211], 0, s[16:17]
	s_mov_b32 m0, s23
	ds_read_b128 v[194:197], v145
	ds_read_b128 v[198:201], v145 offset:1024
	ds_read_b128 v[202:205], v145 offset:2048
	ds_read_b128 v[206:209], v145 offset:3072
	global_load_lds_dwordx4 v[210:211], off
	v_lshl_add_u64 v[210:211], v[212:213], 0, s[16:17]
	s_add_i32 m0, s23, 0x2000
	s_nop 0
	global_load_lds_dwordx4 v[210:211], off
	s_barrier
	s_waitcnt lgkmcnt(0)
	s_setprio 1
	s_waitcnt lgkmcnt(0)
	v_mfma_f32_16x16x32_bf16 v[118:121], v[194:197], v[162:165], v[118:121]
	v_mfma_f32_16x16x32_bf16 v[114:117], v[202:205], v[162:165], v[114:117]
	v_mfma_f32_16x16x32_bf16 v[102:105], v[194:197], v[170:173], v[102:105]
	v_mfma_f32_16x16x32_bf16 v[98:101], v[202:205], v[170:173], v[98:101]
	v_mfma_f32_16x16x32_bf16 v[86:89], v[194:197], v[178:181], v[86:89]
	v_mfma_f32_16x16x32_bf16 v[82:85], v[202:205], v[178:181], v[82:85]
	v_mfma_f32_16x16x32_bf16 v[70:73], v[194:197], v[186:189], v[70:73]
	v_mfma_f32_16x16x32_bf16 v[66:69], v[202:205], v[186:189], v[66:69]
	v_mfma_f32_16x16x32_bf16 v[118:121], v[198:201], v[166:169], v[118:121]
	v_mfma_f32_16x16x32_bf16 v[114:117], v[206:209], v[166:169], v[114:117]
	v_mfma_f32_16x16x32_bf16 v[102:105], v[198:201], v[174:177], v[102:105]
	v_mfma_f32_16x16x32_bf16 v[98:101], v[206:209], v[174:177], v[98:101]
	v_mfma_f32_16x16x32_bf16 v[86:89], v[198:201], v[182:185], v[86:89]
	v_mfma_f32_16x16x32_bf16 v[82:85], v[206:209], v[182:185], v[82:85]
	v_mfma_f32_16x16x32_bf16 v[70:73], v[198:201], v[190:193], v[70:73]
	v_mfma_f32_16x16x32_bf16 v[66:69], v[206:209], v[190:193], v[66:69]
	s_setprio 0
	s_mov_b32 m0, s36
	v_lshl_add_u64 v[210:211], v[214:215], 0, s[16:17]
	s_barrier
	ds_read_b128 v[162:165], v144 offset:49152
	ds_read_b128 v[166:169], v144 offset:50176
	ds_read_b128 v[170:173], v144 offset:51200
	ds_read_b128 v[174:177], v144 offset:52224
	ds_read_b128 v[178:181], v144 offset:53248
	ds_read_b128 v[182:185], v144 offset:54272
	ds_read_b128 v[186:189], v144 offset:55296
	ds_read_b128 v[190:193], v144 offset:56320
	global_load_lds_dwordx4 v[210:211], off
	v_lshl_add_u64 v[210:211], v[216:217], 0, s[16:17]
	s_mov_b32 m0, s37
	s_nop 0
	global_load_lds_dwordx4 v[210:211], off
	s_barrier
; #define PG8_STAGE(bufoff, gbase, voff) do { _Pragma("unroll") for (int _i = 0; _i < 2; ++_i) \
;     __builtin_amdgcn_global_load_lds((const unsigned*)((const char*)(gbase) + (voff)[_i]), (LAS unsigned*)(lds + (bufoff) + ldsw + _i * 8192), 16, 0, 0); } while (0)
; #define PG8_MMA(ai, bj, At, Bt) do { __builtin_amdgcn_s_setprio(1); _Pragma("unroll") for (int m = 0; m < 4; ++m) _Pragma("unroll") for (int n = 0; n < 2; ++n) _Pragma("unroll") for (int k = 0; k < 2; ++k) \
;     acc[ai][bj][m][n] = __builtin_amdgcn_mfma_f32_16x16x32_bf16(Bt[n][k], At[m][k], acc[ai][bj][m][n], 0, 0, 0); __builtin_amdgcn_s_setprio(0); } while (0)
; #define PG8_WAIT_V(n) asm volatile("s_waitcnt vmcnt(" #n ")" ::: "memory")
; #define PG8_WAIT_L(n) asm volatile("s_waitcnt lgkmcnt(" #n ")" ::: "memory")
; #define PG8_BAR __builtin_amdgcn_s_barrier()
; #define PG8_SCHED __builtin_amdgcn_sched_barrier(0)
; template <class Epi>
; __device__ __forceinline__ void gemm_phase(LAS unsigned char* lds, const Gemm g, const StaticOrder& S, const Epi& E) {
;     ...
;       PG8_BAR; PG8_WAIT_L(0); PG8_MMA(1, 0, At, B0); PG8_BAR; PG8_SCHED;
;       PG8_STAGE(PG8_SB(1, 1), b3 + hstepB, voffB);
;       PG8_WAIT_V(6); PG8_BAR; PG8_MMA(1, 1, At, B1); PG8_BAR;
;   __device__ __forceinline__ void operator()(const f32x4 (&acc)[2][2][4][2], const Unit& u, int wr, int wc, int fr, int fq) const {
; #pragma unroll
;     for (int ai = 0; ai < 2; ++ai)
; #pragma unroll
;       for (int m = 0; m < 4; ++m) {
;         const int r = u.pm * 256 + ai * 128 + wr * 64 + m * 16 + fr;
; #pragma unroll
;         for (int bj = 0; bj < 2; ++bj) {
;           float v[8];
; #pragma unroll
;           for (int e = 0; e < 4; ++e) {
;             const float a = fmaxf(acc[ai][bj][m][0][e], 0.f), b = fmaxf(acc[ai][bj][m][1][e], 0.f);
;             v[e] = a * a; v[4 + e] = b * b;
;           }
;           u32x4 w;
; #pragma unroll
;           for (int e = 0; e < 4; ++e) w[e] = cvt_pk_bf16(v[2 * e], v[2 * e + 1]);
;           *(u32x4*)(H + (size_t)r * LDH + u.pn * 256 + bj * 128 + wc * 32 + 8 * fq) = w;
;         }
	s_waitcnt lgkmcnt(0)
	s_setprio 1
	s_waitcnt lgkmcnt(0)
	v_mfma_f32_16x16x32_bf16 v[62:65], v[146:149], v[162:165], v[62:65]
	v_mfma_f32_16x16x32_bf16 v[58:61], v[154:157], v[162:165], v[58:61]
	v_mfma_f32_16x16x32_bf16 v[46:49], v[146:149], v[170:173], v[46:49]
	v_mfma_f32_16x16x32_bf16 v[42:45], v[154:157], v[170:173], v[42:45]
	v_mfma_f32_16x16x32_bf16 v[30:33], v[146:149], v[178:181], v[30:33]
	v_mfma_f32_16x16x32_bf16 v[26:29], v[154:157], v[178:181], v[26:29]
	v_mfma_f32_16x16x32_bf16 v[12:15], v[146:149], v[186:189], v[12:15]
	v_mfma_f32_16x16x32_bf16 v[8:11], v[154:157], v[186:189], v[8:11]
	v_mfma_f32_16x16x32_bf16 v[62:65], v[150:153], v[166:169], v[62:65]
	v_mfma_f32_16x16x32_bf16 v[58:61], v[158:161], v[166:169], v[58:61]
	v_mfma_f32_16x16x32_bf16 v[46:49], v[150:153], v[174:177], v[46:49]
	v_mfma_f32_16x16x32_bf16 v[42:45], v[158:161], v[174:177], v[42:45]
	v_mfma_f32_16x16x32_bf16 v[30:33], v[150:153], v[182:185], v[30:33]
	v_mfma_f32_16x16x32_bf16 v[26:29], v[158:161], v[182:185], v[26:29]
	v_mfma_f32_16x16x32_bf16 v[12:15], v[150:153], v[190:193], v[12:15]
	v_mfma_f32_16x16x32_bf16 v[8:11], v[158:161], v[190:193], v[8:11]
	s_setprio 0
	s_barrier
	s_add_u32 s20, s20, 0x40080
	s_addc_u32 s21, s21, 0
	s_add_i32 s22, s22, s29
	v_lshl_add_u64 v[146:147], s[20:21], 0, v[134:135]
	s_mov_b32 m0, s22
	s_nop 0
	global_load_lds_dwordx4 v[146:147], off
	v_lshl_add_u64 v[146:147], s[20:21], 0, v[130:131]
	s_add_i32 m0, s22, 0x2000
	s_nop 0
	global_load_lds_dwordx4 v[146:147], off
	s_waitcnt vmcnt(6)
	s_barrier
	s_setprio 1
	v_mfma_f32_16x16x32_bf16 v[54:57], v[194:197], v[162:165], v[54:57]
	v_mfma_f32_16x16x32_bf16 v[50:53], v[202:205], v[162:165], v[50:53]
	v_mfma_f32_16x16x32_bf16 v[38:41], v[194:197], v[170:173], v[38:41]
	v_mfma_f32_16x16x32_bf16 v[34:37], v[202:205], v[170:173], v[34:37]
	v_mfma_f32_16x16x32_bf16 v[22:25], v[194:197], v[178:181], v[22:25]
	v_mfma_f32_16x16x32_bf16 v[18:21], v[202:205], v[178:181], v[18:21]
	v_mfma_f32_16x16x32_bf16 v[4:7], v[194:197], v[186:189], v[4:7]
	v_mfma_f32_16x16x32_bf16 v[0:3], v[202:205], v[186:189], v[0:3]
	v_mfma_f32_16x16x32_bf16 v[54:57], v[198:201], v[166:169], v[54:57]
	v_mfma_f32_16x16x32_bf16 v[50:53], v[206:209], v[166:169], v[50:53]
	v_mfma_f32_16x16x32_bf16 v[38:41], v[198:201], v[174:177], v[38:41]
	v_mfma_f32_16x16x32_bf16 v[34:37], v[206:209], v[174:177], v[34:37]
	v_mfma_f32_16x16x32_bf16 v[22:25], v[198:201], v[182:185], v[22:25]
	v_mfma_f32_16x16x32_bf16 v[18:21], v[206:209], v[182:185], v[18:21]
	v_mfma_f32_16x16x32_bf16 v[4:7], v[198:201], v[190:193], v[4:7]
	v_mfma_f32_16x16x32_bf16 v[0:3], v[206:209], v[190:193], v[0:3]
	s_setprio 0
	s_add_i32 s45, s45, 2
	s_add_u32 s14, s14, 0x100
	s_addc_u32 s15, s15, 0
	s_add_u32 s43, s43, 0x100
	s_addc_u32 s44, s44, 0
	s_cmp_gt_u32 s45, 13
	s_barrier
	s_cbranch_scc0 .LBB0_3803
	v_max_f32_e32 v124, v124, v124
	v_max_f32_e32 v126, v126, v126
	v_max_f32_e32 v122, v122, v122
	v_max_f32_e32 v123, v123, v123
	v_max_f32_e32 v124, 0, v124
	v_max_f32_e32 v126, 0, v126
	v_max_f32_e32 v122, 0, v122
	v_max_f32_e32 v127, v127, v127
	v_max_f32_e32 v123, 0, v123
	v_max_f32_e32 v128, v128, v128
	v_mul_f32_e32 v146, v124, v124
	v_max_f32_e32 v124, v129, v129
	v_max_f32_e32 v125, v125, v125
	s_lshl_b32 s14, s39, 8
	v_mul_f32_e32 v126, v126, v126
	v_mul_f32_e32 v122, v122, v122
	v_max_f32_e32 v127, 0, v127
	v_mul_f32_e32 v123, v123, v123
	v_max_f32_e32 v128, 0, v128
	v_max_f32_e32 v124, 0, v124
	v_max_f32_e32 v125, 0, v125
	v_lshl_add_u32 v145, s40, 8, v142
	s_ashr_i32 s15, s14, 31
	v_mul_f32_e32 v127, v127, v127
	v_mul_f32_e32 v128, v128, v128
	v_mul_f32_e32 v129, v124, v124
	v_mul_f32_e32 v147, v125, v125
	v_cvt_pk_bf16_f32 v124, v126, v127
	v_cvt_pk_bf16_f32 v125, v128, v129
	v_cvt_pk_bf16_f32 v126, v122, v123
	v_mov_b64_e32 v[122:123], s[0:1]
	s_movk_i32 s3, 0x2080
	v_mad_i64_i32 v[128:129], s[20:21], v145, s3, v[122:123]
	s_lshl_b64 s[14:15], s[14:15], 1
	v_readlane_b32 s22, v255, 20
	v_lshl_add_u64 v[128:129], v[128:129], 0, s[14:15]
	v_readlane_b32 s23, v255, 21
	v_max_f32_e32 v114, v114, v114
	v_max_f32_e32 v115, v115, v115
	v_lshl_add_u64 v[128:129], v[128:129], 0, s[22:23]
	v_lshl_add_u64 v[128:129], v[128:129], 0, v[16:17]
	v_max_f32_e32 v114, 0, v114
	v_max_f32_e32 v115, 0, v115
	v_max_f32_e32 v116, v116, v116
	v_cvt_pk_bf16_f32 v127, v146, v147
	global_store_dwordx4 v[128:129], v[124:127], off nt
	v_max_f32_e32 v116, 0, v116
	v_max_f32_e32 v118, v118, v118
	v_mul_f32_e32 v124, v114, v114
	v_max_f32_e32 v114, v119, v119
	v_mul_f32_e32 v119, v115, v115
	v_max_f32_e32 v115, v120, v120
	v_max_f32_e32 v114, 0, v114
	v_max_f32_e32 v115, 0, v115
	v_mul_f32_e32 v120, v116, v116
	v_max_f32_e32 v116, v121, v121
	v_max_f32_e32 v117, v117, v117
	v_max_f32_e32 v118, 0, v118
	v_mul_f32_e32 v114, v114, v114
	v_mul_f32_e32 v115, v115, v115
	v_max_f32_e32 v116, 0, v116
	v_max_f32_e32 v117, 0, v117
	v_max_f32_e32 v106, v106, v106
	v_max_f32_e32 v107, v107, v107
	v_max_f32_e32 v108, v108, v108
	v_mul_f32_e32 v118, v118, v118
	v_mul_f32_e32 v116, v116, v116
	v_mul_f32_e32 v117, v117, v117
	v_cvt_pk_bf16_f32 v114, v118, v114
	v_cvt_pk_bf16_f32 v115, v115, v116
	v_max_f32_e32 v106, 0, v106
	v_max_f32_e32 v107, 0, v107
	v_max_f32_e32 v108, 0, v108
	v_cvt_pk_bf16_f32 v116, v124, v119
	v_cvt_pk_bf16_f32 v117, v120, v117
	global_store_dwordx4 v[128:129], v[114:117], off offset:256 nt
	v_max_f32_e32 v110, v110, v110
	v_max_f32_e32 v110, 0, v110
	v_mul_f32_e32 v115, v106, v106
	v_max_f32_e32 v106, v111, v111
	v_mul_f32_e32 v111, v107, v107
	v_max_f32_e32 v107, v112, v112
	v_mul_f32_e32 v112, v108, v108
	v_max_f32_e32 v108, v113, v113
	v_max_f32_e32 v106, 0, v106
;   __device__ __forceinline__ void operator()(const f32x4 (&acc)[2][2][4][2], const Unit& u, int wr, int wc, int fr, int fq) const {
; #pragma unroll
;     for (int ai = 0; ai < 2; ++ai)
; #pragma unroll
;       for (int m = 0; m < 4; ++m) {
;         const int r = u.pm * 256 + ai * 128 + wr * 64 + m * 16 + fr;
; #pragma unroll
;         for (int bj = 0; bj < 2; ++bj) {
;           float v[8];
; #pragma unroll
;           for (int e = 0; e < 4; ++e) {
;             const float a = fmaxf(acc[ai][bj][m][0][e], 0.f), b = fmaxf(acc[ai][bj][m][1][e], 0.f);
;             v[e] = a * a; v[4 + e] = b * b;
;           }
;           u32x4 w;
; #pragma unroll
;           for (int e = 0; e < 4; ++e) w[e] = cvt_pk_bf16(v[2 * e], v[2 * e + 1]);
;           *(u32x4*)(H + (size_t)r * LDH + u.pn * 256 + bj * 128 + wc * 32 + 8 * fq) = w;
;         }
	v_max_f32_e32 v107, 0, v107
	v_max_f32_e32 v108, 0, v108
	v_or_b32_e32 v114, 16, v145
	v_mul_f32_e32 v110, v110, v110
	v_mul_f32_e32 v106, v106, v106
	v_mul_f32_e32 v107, v107, v107
	v_mul_f32_e32 v108, v108, v108
	v_cvt_pk_bf16_f32 v106, v110, v106
	v_cvt_pk_bf16_f32 v107, v107, v108
	v_cvt_pk_bf16_f32 v108, v115, v111
	v_mad_i64_i32 v[110:111], s[20:21], v114, s3, v[122:123]
	v_max_f32_e32 v109, v109, v109
	v_lshl_add_u64 v[110:111], v[110:111], 0, s[14:15]
	v_max_f32_e32 v109, 0, v109
	v_lshl_add_u64 v[110:111], v[110:111], 0, s[22:23]
	v_max_f32_e32 v98, v98, v98
	v_max_f32_e32 v99, v99, v99
	v_mul_f32_e32 v109, v109, v109
	v_lshl_add_u64 v[110:111], v[110:111], 0, v[16:17]
	v_max_f32_e32 v98, 0, v98
	v_max_f32_e32 v99, 0, v99
	v_max_f32_e32 v100, v100, v100
	v_cvt_pk_bf16_f32 v109, v112, v109
	global_store_dwordx4 v[110:111], v[106:109], off nt
	v_max_f32_e32 v100, 0, v100
	v_max_f32_e32 v102, v102, v102
	v_mul_f32_e32 v106, v98, v98
	v_max_f32_e32 v98, v103, v103
	v_mul_f32_e32 v103, v99, v99
	v_max_f32_e32 v99, v104, v104
	v_max_f32_e32 v98, 0, v98
	v_max_f32_e32 v99, 0, v99
	v_mul_f32_e32 v104, v100, v100
	v_max_f32_e32 v100, v105, v105
	v_max_f32_e32 v101, v101, v101
	v_max_f32_e32 v102, 0, v102
	v_mul_f32_e32 v98, v98, v98
	v_mul_f32_e32 v99, v99, v99
	v_max_f32_e32 v100, 0, v100
	v_max_f32_e32 v101, 0, v101
	v_max_f32_e32 v90, v90, v90
	v_max_f32_e32 v91, v91, v91
	v_max_f32_e32 v92, v92, v92
	v_mul_f32_e32 v102, v102, v102
	v_mul_f32_e32 v100, v100, v100
	v_mul_f32_e32 v101, v101, v101
	v_cvt_pk_bf16_f32 v98, v102, v98
	v_cvt_pk_bf16_f32 v99, v99, v100
	v_max_f32_e32 v90, 0, v90
	v_max_f32_e32 v91, 0, v91
	v_max_f32_e32 v92, 0, v92
	v_cvt_pk_bf16_f32 v100, v106, v103
	v_cvt_pk_bf16_f32 v101, v104, v101
	global_store_dwordx4 v[110:111], v[98:101], off offset:256 nt
	v_max_f32_e32 v94, v94, v94
	v_max_f32_e32 v94, 0, v94
	v_mul_f32_e32 v99, v90, v90
	v_max_f32_e32 v90, v95, v95
	v_mul_f32_e32 v95, v91, v91
	v_max_f32_e32 v91, v96, v96
	v_mul_f32_e32 v96, v92, v92
	v_max_f32_e32 v92, v97, v97
	v_max_f32_e32 v90, 0, v90
	v_max_f32_e32 v91, 0, v91
	v_max_f32_e32 v92, 0, v92
	v_or_b32_e32 v98, 32, v145
	v_mul_f32_e32 v94, v94, v94
	v_mul_f32_e32 v90, v90, v90
	v_mul_f32_e32 v91, v91, v91
	v_mul_f32_e32 v92, v92, v92
	v_cvt_pk_bf16_f32 v90, v94, v90
	v_cvt_pk_bf16_f32 v91, v91, v92
	v_cvt_pk_bf16_f32 v92, v99, v95
	v_mad_i64_i32 v[94:95], s[20:21], v98, s3, v[122:123]
	v_max_f32_e32 v93, v93, v93
	v_lshl_add_u64 v[94:95], v[94:95], 0, s[14:15]
	v_max_f32_e32 v93, 0, v93
	v_lshl_add_u64 v[94:95], v[94:95], 0, s[22:23]
	v_max_f32_e32 v82, v82, v82
	v_max_f32_e32 v83, v83, v83
	v_mul_f32_e32 v93, v93, v93
	v_lshl_add_u64 v[94:95], v[94:95], 0, v[16:17]
	v_max_f32_e32 v82, 0, v82
	v_max_f32_e32 v83, 0, v83
	v_max_f32_e32 v84, v84, v84
	v_cvt_pk_bf16_f32 v93, v96, v93
	global_store_dwordx4 v[94:95], v[90:93], off nt
	v_max_f32_e32 v84, 0, v84
	v_max_f32_e32 v86, v86, v86
	v_mul_f32_e32 v90, v82, v82
	v_max_f32_e32 v82, v87, v87
	v_mul_f32_e32 v87, v83, v83
	v_max_f32_e32 v83, v88, v88
	v_max_f32_e32 v82, 0, v82
	v_max_f32_e32 v83, 0, v83
	v_mul_f32_e32 v88, v84, v84
	v_max_f32_e32 v84, v89, v89
	v_max_f32_e32 v85, v85, v85
	v_max_f32_e32 v86, 0, v86
	v_mul_f32_e32 v82, v82, v82
	v_mul_f32_e32 v83, v83, v83
	v_max_f32_e32 v84, 0, v84
	v_max_f32_e32 v85, 0, v85
	v_max_f32_e32 v74, v74, v74
	v_max_f32_e32 v75, v75, v75
	v_max_f32_e32 v76, v76, v76
	v_mul_f32_e32 v86, v86, v86
	v_mul_f32_e32 v84, v84, v84
	v_mul_f32_e32 v85, v85, v85
	v_cvt_pk_bf16_f32 v82, v86, v82
	v_cvt_pk_bf16_f32 v83, v83, v84
	v_max_f32_e32 v74, 0, v74
	v_max_f32_e32 v75, 0, v75
	v_max_f32_e32 v76, 0, v76
	v_cvt_pk_bf16_f32 v84, v90, v87
	v_cvt_pk_bf16_f32 v85, v88, v85
	global_store_dwordx4 v[94:95], v[82:85], off offset:256 nt
	v_max_f32_e32 v78, v78, v78
	v_max_f32_e32 v78, 0, v78
	v_mul_f32_e32 v83, v74, v74
	v_max_f32_e32 v74, v79, v79
	v_mul_f32_e32 v79, v75, v75
	v_max_f32_e32 v75, v80, v80
	v_mul_f32_e32 v80, v76, v76
	v_max_f32_e32 v76, v81, v81
	v_max_f32_e32 v74, 0, v74
	v_max_f32_e32 v75, 0, v75
	v_max_f32_e32 v76, 0, v76
	v_or_b32_e32 v82, 48, v145
	v_mul_f32_e32 v78, v78, v78
	v_mul_f32_e32 v74, v74, v74
	v_mul_f32_e32 v75, v75, v75
	v_mul_f32_e32 v76, v76, v76
	v_cvt_pk_bf16_f32 v74, v78, v74
	v_cvt_pk_bf16_f32 v75, v75, v76
	v_cvt_pk_bf16_f32 v76, v83, v79
	v_mad_i64_i32 v[78:79], s[20:21], v82, s3, v[122:123]
	v_max_f32_e32 v77, v77, v77
	v_lshl_add_u64 v[78:79], v[78:79], 0, s[14:15]
	v_max_f32_e32 v77, 0, v77
	v_lshl_add_u64 v[78:79], v[78:79], 0, s[22:23]
	v_max_f32_e32 v66, v66, v66
	v_max_f32_e32 v67, v67, v67
	v_mul_f32_e32 v77, v77, v77
	v_lshl_add_u64 v[78:79], v[78:79], 0, v[16:17]
	v_max_f32_e32 v66, 0, v66
	v_max_f32_e32 v67, 0, v67
	v_max_f32_e32 v68, v68, v68
	v_cvt_pk_bf16_f32 v77, v80, v77
	global_store_dwordx4 v[78:79], v[74:77], off nt
	v_max_f32_e32 v68, 0, v68
	v_max_f32_e32 v70, v70, v70
	v_mul_f32_e32 v74, v66, v66
	v_max_f32_e32 v66, v71, v71
	v_mul_f32_e32 v71, v67, v67
	v_max_f32_e32 v67, v72, v72
	v_max_f32_e32 v66, 0, v66
	v_max_f32_e32 v67, 0, v67
	v_mul_f32_e32 v72, v68, v68
	v_max_f32_e32 v68, v73, v73
	v_max_f32_e32 v69, v69, v69
	v_max_f32_e32 v70, 0, v70
	v_mul_f32_e32 v66, v66, v66
	v_mul_f32_e32 v67, v67, v67
	v_max_f32_e32 v68, 0, v68
	v_max_f32_e32 v69, 0, v69
	v_max_f32_e32 v58, v58, v58
	v_max_f32_e32 v59, v59, v59
	v_max_f32_e32 v60, v60, v60
	v_mul_f32_e32 v70, v70, v70
	v_mul_f32_e32 v68, v68, v68
	v_mul_f32_e32 v69, v69, v69
	v_cvt_pk_bf16_f32 v66, v70, v66
	v_cvt_pk_bf16_f32 v67, v67, v68
	v_max_f32_e32 v58, 0, v58
	v_max_f32_e32 v59, 0, v59
	v_max_f32_e32 v60, 0, v60
	v_cvt_pk_bf16_f32 v68, v74, v71
;   __device__ __forceinline__ void operator()(const f32x4 (&acc)[2][2][4][2], const Unit& u, int wr, int wc, int fr, int fq) const {
; #pragma unroll
;     for (int ai = 0; ai < 2; ++ai)
; #pragma unroll
;       for (int m = 0; m < 4; ++m) {
;         const int r = u.pm * 256 + ai * 128 + wr * 64 + m * 16 + fr;
; #pragma unroll
;         for (int bj = 0; bj < 2; ++bj) {
;           float v[8];
; #pragma unroll
;           for (int e = 0; e < 4; ++e) {
;             const float a = fmaxf(acc[ai][bj][m][0][e], 0.f), b = fmaxf(acc[ai][bj][m][1][e], 0.f);
;             v[e] = a * a; v[4 + e] = b * b;
;           }
;           u32x4 w;
; #pragma unroll
;           for (int e = 0; e < 4; ++e) w[e] = cvt_pk_bf16(v[2 * e], v[2 * e + 1]);
;           *(u32x4*)(H + (size_t)r * LDH + u.pn * 256 + bj * 128 + wc * 32 + 8 * fq) = w;
;         }
	v_cvt_pk_bf16_f32 v69, v72, v69
	global_store_dwordx4 v[78:79], v[66:69], off offset:256 nt
	v_max_f32_e32 v62, v62, v62
	v_max_f32_e32 v62, 0, v62
	v_mul_f32_e32 v67, v58, v58
	v_max_f32_e32 v58, v63, v63
	v_mul_f32_e32 v63, v59, v59
	v_max_f32_e32 v59, v64, v64
	v_mul_f32_e32 v64, v60, v60
	v_max_f32_e32 v60, v65, v65
	v_max_f32_e32 v58, 0, v58
	v_max_f32_e32 v59, 0, v59
	v_max_f32_e32 v60, 0, v60
	v_add_u32_e32 v66, 0x80, v145
	v_mul_f32_e32 v62, v62, v62
	v_mul_f32_e32 v58, v58, v58
	v_mul_f32_e32 v59, v59, v59
	v_mul_f32_e32 v60, v60, v60
	v_cvt_pk_bf16_f32 v58, v62, v58
	v_cvt_pk_bf16_f32 v59, v59, v60
	v_cvt_pk_bf16_f32 v60, v67, v63
	v_mad_i64_i32 v[62:63], s[20:21], v66, s3, v[122:123]
	v_max_f32_e32 v61, v61, v61
	v_lshl_add_u64 v[62:63], v[62:63], 0, s[14:15]
	v_max_f32_e32 v61, 0, v61
	v_lshl_add_u64 v[62:63], v[62:63], 0, s[22:23]
	v_max_f32_e32 v50, v50, v50
	v_max_f32_e32 v51, v51, v51
	v_mul_f32_e32 v61, v61, v61
	v_lshl_add_u64 v[62:63], v[62:63], 0, v[16:17]
	v_max_f32_e32 v50, 0, v50
	v_max_f32_e32 v51, 0, v51
	v_max_f32_e32 v52, v52, v52
	v_cvt_pk_bf16_f32 v61, v64, v61
	global_store_dwordx4 v[62:63], v[58:61], off nt
	v_max_f32_e32 v52, 0, v52
	v_max_f32_e32 v54, v54, v54
	v_mul_f32_e32 v58, v50, v50
	v_max_f32_e32 v50, v55, v55
	v_mul_f32_e32 v55, v51, v51
	v_max_f32_e32 v51, v56, v56
	v_max_f32_e32 v50, 0, v50
	v_max_f32_e32 v51, 0, v51
	v_mul_f32_e32 v56, v52, v52
	v_max_f32_e32 v52, v57, v57
	v_max_f32_e32 v53, v53, v53
	v_max_f32_e32 v54, 0, v54
	v_mul_f32_e32 v50, v50, v50
	v_mul_f32_e32 v51, v51, v51
	v_max_f32_e32 v52, 0, v52
	v_max_f32_e32 v53, 0, v53
	v_max_f32_e32 v42, v42, v42
	v_max_f32_e32 v43, v43, v43
	v_max_f32_e32 v44, v44, v44
	v_mul_f32_e32 v54, v54, v54
	v_mul_f32_e32 v52, v52, v52
	v_mul_f32_e32 v53, v53, v53
	v_cvt_pk_bf16_f32 v50, v54, v50
	v_cvt_pk_bf16_f32 v51, v51, v52
	v_max_f32_e32 v42, 0, v42
	v_max_f32_e32 v43, 0, v43
	v_max_f32_e32 v44, 0, v44
	v_cvt_pk_bf16_f32 v52, v58, v55
	v_cvt_pk_bf16_f32 v53, v56, v53
	global_store_dwordx4 v[62:63], v[50:53], off offset:256 nt
	v_max_f32_e32 v46, v46, v46
	v_max_f32_e32 v46, 0, v46
	v_mul_f32_e32 v51, v42, v42
	v_max_f32_e32 v42, v47, v47
	v_mul_f32_e32 v47, v43, v43
	v_max_f32_e32 v43, v48, v48
	v_mul_f32_e32 v48, v44, v44
	v_max_f32_e32 v44, v49, v49
	v_max_f32_e32 v42, 0, v42
	v_max_f32_e32 v43, 0, v43
	v_max_f32_e32 v44, 0, v44
	v_add_u32_e32 v50, 0x90, v145
	v_mul_f32_e32 v46, v46, v46
	v_mul_f32_e32 v42, v42, v42
	v_mul_f32_e32 v43, v43, v43
	v_mul_f32_e32 v44, v44, v44
	v_cvt_pk_bf16_f32 v42, v46, v42
	v_cvt_pk_bf16_f32 v43, v43, v44
	v_cvt_pk_bf16_f32 v44, v51, v47
	v_mad_i64_i32 v[46:47], s[20:21], v50, s3, v[122:123]
	v_max_f32_e32 v45, v45, v45
	v_lshl_add_u64 v[46:47], v[46:47], 0, s[14:15]
	v_max_f32_e32 v45, 0, v45
	v_lshl_add_u64 v[46:47], v[46:47], 0, s[22:23]
	v_max_f32_e32 v34, v34, v34
	v_max_f32_e32 v35, v35, v35
	v_mul_f32_e32 v45, v45, v45
	v_lshl_add_u64 v[46:47], v[46:47], 0, v[16:17]
	v_max_f32_e32 v34, 0, v34
	v_max_f32_e32 v35, 0, v35
	v_max_f32_e32 v36, v36, v36
	v_cvt_pk_bf16_f32 v45, v48, v45
	global_store_dwordx4 v[46:47], v[42:45], off nt
	v_max_f32_e32 v36, 0, v36
	v_max_f32_e32 v38, v38, v38
	v_mul_f32_e32 v42, v34, v34
	v_max_f32_e32 v34, v39, v39
	v_mul_f32_e32 v39, v35, v35
	v_max_f32_e32 v35, v40, v40
	v_max_f32_e32 v34, 0, v34
	v_max_f32_e32 v35, 0, v35
	v_mul_f32_e32 v40, v36, v36
	v_max_f32_e32 v36, v41, v41
	v_max_f32_e32 v37, v37, v37
	v_max_f32_e32 v38, 0, v38
	v_mul_f32_e32 v34, v34, v34
	v_mul_f32_e32 v35, v35, v35
	v_max_f32_e32 v36, 0, v36
	v_max_f32_e32 v37, 0, v37
	v_max_f32_e32 v26, v26, v26
	v_max_f32_e32 v27, v27, v27
	v_max_f32_e32 v28, v28, v28
	v_mul_f32_e32 v38, v38, v38
	v_mul_f32_e32 v36, v36, v36
	v_mul_f32_e32 v37, v37, v37
	v_cvt_pk_bf16_f32 v34, v38, v34
	v_cvt_pk_bf16_f32 v35, v35, v36
	v_max_f32_e32 v26, 0, v26
	v_max_f32_e32 v27, 0, v27
	v_max_f32_e32 v28, 0, v28
	v_cvt_pk_bf16_f32 v36, v42, v39
;   __device__ __forceinline__ void operator()(const f32x4 (&acc)[2][2][4][2], const Unit& u, int wr, int wc, int fr, int fq) const {
; #pragma unroll
;     for (int ai = 0; ai < 2; ++ai)
; #pragma unroll
;       for (int m = 0; m < 4; ++m) {
;         const int r = u.pm * 256 + ai * 128 + wr * 64 + m * 16 + fr;
; #pragma unroll
;         for (int bj = 0; bj < 2; ++bj) {
;           float v[8];
; #pragma unroll
;           for (int e = 0; e < 4; ++e) {
;             const float a = fmaxf(acc[ai][bj][m][0][e], 0.f), b = fmaxf(acc[ai][bj][m][1][e], 0.f);
;             v[e] = a * a; v[4 + e] = b * b;
;           }
;           u32x4 w;
; #pragma unroll
;           for (int e = 0; e < 4; ++e) w[e] = cvt_pk_bf16(v[2 * e], v[2 * e + 1]);
;           *(u32x4*)(H + (size_t)r * LDH + u.pn * 256 + bj * 128 + wc * 32 + 8 * fq) = w;
;         }
	v_cvt_pk_bf16_f32 v37, v40, v37
	global_store_dwordx4 v[46:47], v[34:37], off offset:256 nt
	v_max_f32_e32 v30, v30, v30
	v_max_f32_e32 v30, 0, v30
	v_mul_f32_e32 v35, v26, v26
	v_max_f32_e32 v26, v31, v31
	v_mul_f32_e32 v31, v27, v27
	v_max_f32_e32 v27, v32, v32
	v_mul_f32_e32 v32, v28, v28
	v_max_f32_e32 v28, v33, v33
	v_max_f32_e32 v26, 0, v26
	v_max_f32_e32 v27, 0, v27
	v_max_f32_e32 v28, 0, v28
	v_add_u32_e32 v34, 0xa0, v145
	v_mul_f32_e32 v30, v30, v30
	v_mul_f32_e32 v26, v26, v26
	v_mul_f32_e32 v27, v27, v27
	v_mul_f32_e32 v28, v28, v28
	v_cvt_pk_bf16_f32 v26, v30, v26
	v_cvt_pk_bf16_f32 v27, v27, v28
	v_cvt_pk_bf16_f32 v28, v35, v31
	v_mad_i64_i32 v[30:31], s[20:21], v34, s3, v[122:123]
	v_max_f32_e32 v29, v29, v29
	v_lshl_add_u64 v[30:31], v[30:31], 0, s[14:15]
	v_max_f32_e32 v29, 0, v29
	v_lshl_add_u64 v[30:31], v[30:31], 0, s[22:23]
	v_max_f32_e32 v18, v18, v18
	v_max_f32_e32 v19, v19, v19
	v_mul_f32_e32 v29, v29, v29
	v_lshl_add_u64 v[30:31], v[30:31], 0, v[16:17]
	v_max_f32_e32 v18, 0, v18
	v_max_f32_e32 v19, 0, v19
	v_max_f32_e32 v20, v20, v20
	v_cvt_pk_bf16_f32 v29, v32, v29
	global_store_dwordx4 v[30:31], v[26:29], off nt
	v_max_f32_e32 v20, 0, v20
	v_max_f32_e32 v22, v22, v22
	v_mul_f32_e32 v26, v18, v18
	v_max_f32_e32 v18, v23, v23
	v_mul_f32_e32 v23, v19, v19
	v_max_f32_e32 v19, v24, v24
	v_max_f32_e32 v18, 0, v18
	v_max_f32_e32 v19, 0, v19
	v_mul_f32_e32 v24, v20, v20
	v_max_f32_e32 v20, v25, v25
	v_max_f32_e32 v21, v21, v21
	v_max_f32_e32 v22, 0, v22
	v_mul_f32_e32 v18, v18, v18
	v_mul_f32_e32 v19, v19, v19
	v_max_f32_e32 v20, 0, v20
	v_max_f32_e32 v21, 0, v21
	v_max_f32_e32 v8, v8, v8
	v_max_f32_e32 v9, v9, v9
	v_max_f32_e32 v10, v10, v10
	v_mul_f32_e32 v22, v22, v22
	v_mul_f32_e32 v20, v20, v20
	v_mul_f32_e32 v21, v21, v21
	v_cvt_pk_bf16_f32 v18, v22, v18
	v_cvt_pk_bf16_f32 v19, v19, v20
	v_max_f32_e32 v8, 0, v8
	v_max_f32_e32 v9, 0, v9
	v_max_f32_e32 v10, 0, v10
	v_cvt_pk_bf16_f32 v20, v26, v23
	v_cvt_pk_bf16_f32 v21, v24, v21
	global_store_dwordx4 v[30:31], v[18:21], off offset:256 nt
	v_max_f32_e32 v12, v12, v12
	v_max_f32_e32 v12, 0, v12
	v_mul_f32_e32 v19, v8, v8
	v_max_f32_e32 v8, v13, v13
	v_mul_f32_e32 v13, v9, v9
	v_max_f32_e32 v9, v14, v14
	v_mul_f32_e32 v14, v10, v10
	v_max_f32_e32 v10, v15, v15
	v_max_f32_e32 v8, 0, v8
	v_max_f32_e32 v9, 0, v9
	v_max_f32_e32 v10, 0, v10
	v_add_u32_e32 v18, 0xb0, v145
	v_mul_f32_e32 v12, v12, v12
	v_mul_f32_e32 v8, v8, v8
	v_mul_f32_e32 v9, v9, v9
	v_mul_f32_e32 v10, v10, v10
	v_cvt_pk_bf16_f32 v8, v12, v8
	v_cvt_pk_bf16_f32 v9, v9, v10
	v_cvt_pk_bf16_f32 v10, v19, v13
	v_mad_i64_i32 v[12:13], s[20:21], v18, s3, v[122:123]
	v_max_f32_e32 v11, v11, v11
	v_lshl_add_u64 v[12:13], v[12:13], 0, s[14:15]
	v_max_f32_e32 v11, 0, v11
	v_lshl_add_u64 v[12:13], v[12:13], 0, s[22:23]
	v_max_f32_e32 v0, v0, v0
	v_max_f32_e32 v1, v1, v1
	v_max_f32_e32 v2, v2, v2
	v_mul_f32_e32 v11, v11, v11
	v_lshl_add_u64 v[12:13], v[12:13], 0, v[16:17]
	v_max_f32_e32 v0, 0, v0
	v_max_f32_e32 v1, 0, v1
	v_max_f32_e32 v2, 0, v2
	v_cvt_pk_bf16_f32 v11, v14, v11
	global_store_dwordx4 v[12:13], v[8:11], off nt
	v_max_f32_e32 v3, v3, v3
	v_max_f32_e32 v4, v4, v4
	v_mul_f32_e32 v8, v0, v0
	v_max_f32_e32 v0, v5, v5
	v_mul_f32_e32 v5, v1, v1
	v_max_f32_e32 v1, v6, v6
	v_mul_f32_e32 v6, v2, v2
	v_max_f32_e32 v2, v7, v7
	v_max_f32_e32 v0, 0, v0
	v_max_f32_e32 v1, 0, v1
	v_max_f32_e32 v2, 0, v2
	v_max_f32_e32 v3, 0, v3
	v_max_f32_e32 v4, 0, v4
	v_mul_f32_e32 v0, v0, v0
	v_mul_f32_e32 v1, v1, v1
	v_mul_f32_e32 v2, v2, v2
	v_mul_f32_e32 v3, v3, v3
	s_and_b64 vcc, exec, s[6:7]
	s_mov_b32 s39, s2
	s_mov_b32 s40, s4
	s_mov_b64 s[20:21], s[12:13]
	s_mov_b64 s[14:15], s[10:11]
	v_mul_f32_e32 v4, v4, v4
	v_cvt_pk_bf16_f32 v0, v4, v0
	v_cvt_pk_bf16_f32 v1, v1, v2
	v_cvt_pk_bf16_f32 v2, v8, v5
	v_cvt_pk_bf16_f32 v3, v6, v3
	global_store_dwordx4 v[12:13], v[0:3], off offset:256 nt
	s_cbranch_vccz .LBB0_3794
	s_branch .LBB0_3806
